# v017 + FFN-down residual epilogue: 11 residual loads issued up front (SGPR-base form) instead of load+vmcnt(0) per row group
# baseline (speedup 1.0000x reference)
.LBB0_356:
	v_lshl_add_u32 v144, s11, 8, v1
	v_ashrrev_i32_e32 v145, 31, v144
	v_lshl_or_b32 v142, s10, 8, v147
	v_lshlrev_b64 v[140:141], 12, v[144:145]
	v_ashrrev_i32_e32 v143, 31, v142
	v_lshl_add_u64 v[140:141], s[94:95], 0, v[140:141]
	v_lshl_add_u64 v[140:141], v[142:143], 1, v[140:141]
	global_load_dwordx4 v[150:153], v[140:141], off
	v_lshlrev_b32_e32 v206, 12, v144
	v_lshl_add_u32 v206, v142, 1, v206
	s_add_u32 s100, s94, 0x10000
	s_addc_u32 s101, s95, 0
	global_load_dwordx4 v[182:185], v206, s[100:101]
	s_add_u32 s100, s94, 0x20000
	s_addc_u32 s101, s95, 0
	global_load_dwordx4 v[186:189], v206, s[100:101]
	s_add_u32 s100, s94, 0x30000
	s_addc_u32 s101, s95, 0
	global_load_dwordx4 v[190:193], v206, s[100:101]
	s_add_u32 s100, s94, 0x80000
	s_addc_u32 s101, s95, 0
	global_load_dwordx4 v[194:197], v206, s[100:101]
	global_load_dwordx4 v[198:201], v206, s[100:101] offset:256
	s_add_u32 s100, s94, 0x90000
	s_addc_u32 s101, s95, 0
	global_load_dwordx4 v[202:205], v206, s[100:101]
	global_load_dwordx4 v[216:219], v206, s[100:101] offset:256
	s_add_u32 s100, s94, 0xa0000
	s_addc_u32 s101, s95, 0
	global_load_dwordx4 v[220:223], v206, s[100:101]
	global_load_dwordx4 v[224:227], v206, s[100:101] offset:256
	s_add_u32 s100, s94, 0xb0000
	s_addc_u32 s101, s95, 0
	global_load_dwordx4 v[228:231], v206, s[100:101]
	global_load_dwordx4 v[232:235], v206, s[100:101] offset:256
	s_waitcnt vmcnt(11)
	v_lshlrev_b32_e32 v149, 16, v150
	v_and_b32_e32 v150, 0xffff0000, v150
	v_lshlrev_b32_e32 v154, 16, v151
	v_and_b32_e32 v151, 0xffff0000, v151
	v_lshlrev_b32_e32 v155, 16, v152
	v_and_b32_e32 v152, 0xffff0000, v152
	v_lshlrev_b32_e32 v156, 16, v153
	v_and_b32_e32 v153, 0xffff0000, v153
	v_fmac_f32_e32 v150, 0.5, v127
	v_fmac_f32_e32 v151, 0.5, v129
	v_fmac_f32_e32 v152, 0.5, v123
	v_fmac_f32_e32 v153, 0.5, v125
	v_fmac_f32_e32 v149, 0.5, v126
	v_fmac_f32_e32 v154, 0.5, v128
	v_fmac_f32_e32 v155, 0.5, v122
	v_fmac_f32_e32 v156, 0.5, v124
	v_cvt_pk_bf16_f32 v124, v149, v150
	v_cvt_pk_bf16_f32 v125, v154, v151
	v_cvt_pk_bf16_f32 v126, v155, v152
	v_cvt_pk_bf16_f32 v127, v156, v153
	global_load_dwordx4 v[150:153], v[140:141], off offset:256
	v_lshlrev_b32_e32 v128, 16, v124
	global_store_dwordx4 v[140:141], v[124:127], off
	v_lshlrev_b32_e32 v129, 16, v125
	v_lshlrev_b32_e32 v149, 16, v126
	v_and_b32_e32 v124, 0xffff0000, v124
	v_and_b32_e32 v125, 0xffff0000, v125
	v_and_b32_e32 v126, 0xffff0000, v126
	v_lshlrev_b32_e32 v154, 16, v127
	v_and_b32_e32 v127, 0xffff0000, v127
	v_mul_f32_e32 v124, v124, v124
	v_mul_f32_e32 v125, v125, v125
	v_mul_f32_e32 v126, v126, v126
	v_mul_f32_e32 v127, v127, v127
	v_fmac_f32_e32 v124, v128, v128
	v_fmac_f32_e32 v125, v129, v129
	v_fmac_f32_e32 v126, v149, v149
	v_fmac_f32_e32 v127, v154, v154
	v_add_f32_e32 v124, v124, v125
	v_add_f32_e32 v125, v126, v127
	v_add_f32_e32 v128, v124, v125
	v_and_b32_e32 v123, 64, v212
	v_xor_b32_e32 v122, 16, v212
	v_add_u32_e32 v123, 64, v123
	v_cmp_lt_i32_e32 vcc, v122, v123
	s_waitcnt vmcnt(1)
	v_lshlrev_b32_e32 v124, 16, v150
	v_and_b32_e32 v125, 0xffff0000, v150
	v_lshlrev_b32_e32 v126, 16, v151
	v_and_b32_e32 v127, 0xffff0000, v151
	v_lshlrev_b32_e32 v129, 16, v152
	v_and_b32_e32 v149, 0xffff0000, v152
	v_lshlrev_b32_e32 v150, 16, v153
	v_and_b32_e32 v151, 0xffff0000, v153
	v_fmac_f32_e32 v124, 0.5, v118
	v_fmac_f32_e32 v125, 0.5, v119
	v_fmac_f32_e32 v126, 0.5, v120
	v_fmac_f32_e32 v127, 0.5, v121
	v_fmac_f32_e32 v129, 0.5, v114
	v_fmac_f32_e32 v149, 0.5, v115
	v_fmac_f32_e32 v150, 0.5, v116
	v_fmac_f32_e32 v151, 0.5, v117
	v_cvt_pk_bf16_f32 v124, v124, v125
	v_cvt_pk_bf16_f32 v125, v126, v127
	v_cvt_pk_bf16_f32 v126, v129, v149
	v_cvt_pk_bf16_f32 v127, v150, v151
	v_cndmask_b32_e32 v122, v212, v122, vcc
	v_and_b32_e32 v115, 0xffff0000, v124
	v_and_b32_e32 v117, 0xffff0000, v125
	v_and_b32_e32 v119, 0xffff0000, v126
	v_and_b32_e32 v121, 0xffff0000, v127
	v_lshlrev_b32_e32 v114, 16, v124
	v_lshlrev_b32_e32 v116, 16, v125
	v_lshlrev_b32_e32 v118, 16, v126
	v_lshlrev_b32_e32 v120, 16, v127
	v_mul_f32_e32 v115, v115, v115
	v_mul_f32_e32 v117, v117, v117
	v_mul_f32_e32 v119, v119, v119
	v_mul_f32_e32 v121, v121, v121
	v_fmac_f32_e32 v115, v114, v114
	v_fmac_f32_e32 v117, v116, v116
	v_fmac_f32_e32 v119, v118, v118
	v_fmac_f32_e32 v121, v120, v120
	v_add_f32_e32 v114, v115, v117
	v_add_f32_e32 v115, v119, v121
	v_add_f32_e32 v114, v114, v115
	v_lshlrev_b32_e32 v122, 2, v122
	v_add_f32_e32 v114, v128, v114
	ds_bpermute_b32 v115, v122, v114
	v_xor_b32_e32 v116, 32, v212
	v_cmp_lt_i32_e32 vcc, v116, v123
	global_store_dwordx4 v[140:141], v[124:127], off offset:256
	s_waitcnt lgkmcnt(0)
	v_add_f32_e32 v117, v114, v115
	v_cndmask_b32_e32 v116, v212, v116, vcc
	v_lshlrev_b32_e32 v116, 2, v116
	ds_bpermute_b32 v118, v116, v117
	v_lshl_add_u64 v[114:115], v[144:145], 3, s[8:9]
	s_and_saveexec_b64 s[0:1], s[40:41]
	s_cbranch_execz .LBB0_358
	s_waitcnt lgkmcnt(0)
	v_add_f32_e32 v117, v117, v118
	v_fma_f32 v117, v117, s6, 0.5
	v_trunc_f32_e32 v117, v117
	v_mul_f32_e32 v118, 0x2f800000, v117
	v_floor_f32_e32 v119, v118
	v_fmac_f32_e32 v117, 0xcf800000, v119
	v_cvt_u32_f32_e32 v118, v117
	v_cvt_u32_f32_e32 v119, v119
	v_mov_b32_e32 v168, v118
	v_mov_b32_e32 v169, v119
.LBB0_358:
	s_or_b64 exec, exec, s[0:1]
	s_waitcnt lgkmcnt(0)
	v_or_b32_e32 v118, 16, v144
	v_ashrrev_i32_e32 v119, 31, v118
	v_lshlrev_b64 v[118:119], 12, v[118:119]
	v_lshl_add_u64 v[118:119], s[94:95], 0, v[118:119]
	v_lshl_add_u64 v[124:125], v[142:143], 1, v[118:119]
	v_mov_b32_e32 v118, v182
	v_mov_b32_e32 v119, v183
	v_mov_b32_e32 v120, v184
	v_mov_b32_e32 v121, v185
	v_lshlrev_b32_e32 v117, 16, v118
	v_and_b32_e32 v118, 0xffff0000, v118
	v_lshlrev_b32_e32 v123, 16, v119
	v_and_b32_e32 v119, 0xffff0000, v119
	v_lshlrev_b32_e32 v126, 16, v120
	v_and_b32_e32 v120, 0xffff0000, v120
	v_lshlrev_b32_e32 v127, 16, v121
	v_and_b32_e32 v121, 0xffff0000, v121
	v_fmac_f32_e32 v117, 0.5, v110
	v_fmac_f32_e32 v118, 0.5, v111
	v_fmac_f32_e32 v123, 0.5, v112
	v_fmac_f32_e32 v119, 0.5, v113
	v_fmac_f32_e32 v126, 0.5, v106
	v_fmac_f32_e32 v120, 0.5, v107
	v_fmac_f32_e32 v127, 0.5, v108
	v_fmac_f32_e32 v121, 0.5, v109
	v_cvt_pk_bf16_f32 v106, v117, v118
	v_cvt_pk_bf16_f32 v107, v123, v119
	v_cvt_pk_bf16_f32 v108, v126, v120
	v_cvt_pk_bf16_f32 v109, v127, v121
	global_load_dwordx4 v[110:113], v[124:125], off offset:256
	v_lshlrev_b32_e32 v117, 16, v106
	global_store_dwordx4 v[124:125], v[106:109], off
	v_lshlrev_b32_e32 v118, 16, v107
	v_lshlrev_b32_e32 v119, 16, v108
	v_and_b32_e32 v106, 0xffff0000, v106
	v_and_b32_e32 v107, 0xffff0000, v107
	v_and_b32_e32 v108, 0xffff0000, v108
	v_lshlrev_b32_e32 v120, 16, v109
	v_and_b32_e32 v109, 0xffff0000, v109
	v_mul_f32_e32 v106, v106, v106
	v_mul_f32_e32 v107, v107, v107
	v_mul_f32_e32 v108, v108, v108
	v_mul_f32_e32 v109, v109, v109
	v_fmac_f32_e32 v106, v117, v117
	v_fmac_f32_e32 v107, v118, v118
	v_fmac_f32_e32 v108, v119, v119
	v_fmac_f32_e32 v109, v120, v120
	v_add_f32_e32 v106, v106, v107
	v_add_f32_e32 v107, v108, v109
	v_add_f32_e32 v106, v106, v107
	s_waitcnt vmcnt(1)
	v_lshlrev_b32_e32 v107, 16, v110
	v_and_b32_e32 v108, 0xffff0000, v110
	v_and_b32_e32 v110, 0xffff0000, v111
	v_lshlrev_b32_e32 v109, 16, v111
	v_lshlrev_b32_e32 v111, 16, v112
	v_and_b32_e32 v112, 0xffff0000, v112
	v_lshlrev_b32_e32 v117, 16, v113
	v_and_b32_e32 v113, 0xffff0000, v113
	v_fmac_f32_e32 v108, 0.5, v103
	v_fmac_f32_e32 v110, 0.5, v105
	v_fmac_f32_e32 v107, 0.5, v102
	v_fmac_f32_e32 v109, 0.5, v104
	v_fmac_f32_e32 v111, 0.5, v98
	v_fmac_f32_e32 v112, 0.5, v99
	v_fmac_f32_e32 v117, 0.5, v100
	v_fmac_f32_e32 v113, 0.5, v101
	v_cvt_pk_bf16_f32 v100, v107, v108
	v_cvt_pk_bf16_f32 v101, v109, v110
	v_cvt_pk_bf16_f32 v102, v111, v112
	v_cvt_pk_bf16_f32 v103, v117, v113
	global_store_dwordx4 v[124:125], v[100:103], off offset:256
	v_and_b32_e32 v99, 0xffff0000, v100
	v_and_b32_e32 v105, 0xffff0000, v101
	v_and_b32_e32 v108, 0xffff0000, v102
	v_and_b32_e32 v110, 0xffff0000, v103
	v_lshlrev_b32_e32 v98, 16, v100
	v_lshlrev_b32_e32 v104, 16, v101
	v_lshlrev_b32_e32 v107, 16, v102
	v_lshlrev_b32_e32 v109, 16, v103
	v_mul_f32_e32 v99, v99, v99
	v_mul_f32_e32 v105, v105, v105
	v_mul_f32_e32 v108, v108, v108
	v_mul_f32_e32 v110, v110, v110
	v_fmac_f32_e32 v99, v98, v98
	v_fmac_f32_e32 v105, v104, v104
	v_fmac_f32_e32 v108, v107, v107
	v_fmac_f32_e32 v110, v109, v109
	v_add_f32_e32 v98, v99, v105
	v_add_f32_e32 v99, v108, v110
	v_add_f32_e32 v98, v98, v99
	v_add_f32_e32 v98, v106, v98
	ds_bpermute_b32 v99, v122, v98
	s_waitcnt lgkmcnt(0)
	v_add_f32_e32 v98, v98, v99
	ds_bpermute_b32 v99, v116, v98
	s_and_saveexec_b64 s[0:1], s[40:41]
	s_cbranch_execz .LBB0_360
	s_waitcnt lgkmcnt(0)
	v_add_f32_e32 v98, v98, v99
	v_fma_f32 v98, v98, s6, 0.5
	v_trunc_f32_e32 v98, v98
	v_mul_f32_e32 v99, 0x2f800000, v98
	v_floor_f32_e32 v99, v99
	v_fmac_f32_e32 v98, 0xcf800000, v99
	v_cvt_u32_f32_e32 v98, v98
	v_cvt_u32_f32_e32 v99, v99
	v_mov_b32_e32 v170, v98
	v_mov_b32_e32 v171, v99
.LBB0_360:
	s_or_b64 exec, exec, s[0:1]
	v_or_b32_e32 v98, 32, v144
	s_waitcnt lgkmcnt(0)
	v_ashrrev_i32_e32 v99, 31, v98
	v_lshlrev_b64 v[98:99], 12, v[98:99]
	v_lshl_add_u64 v[98:99], s[94:95], 0, v[98:99]
	v_lshl_add_u64 v[102:103], v[142:143], 1, v[98:99]
	v_mov_b32_e32 v98, v186
	v_mov_b32_e32 v99, v187
	v_mov_b32_e32 v100, v188
	v_mov_b32_e32 v101, v189
	v_lshlrev_b32_e32 v104, 16, v98
	v_and_b32_e32 v98, 0xffff0000, v98
	v_lshlrev_b32_e32 v105, 16, v99
	v_and_b32_e32 v99, 0xffff0000, v99
	v_lshlrev_b32_e32 v106, 16, v100
	v_and_b32_e32 v100, 0xffff0000, v100
	v_lshlrev_b32_e32 v107, 16, v101
	v_and_b32_e32 v101, 0xffff0000, v101
	v_fmac_f32_e32 v104, 0.5, v94
	v_fmac_f32_e32 v98, 0.5, v95
	v_fmac_f32_e32 v105, 0.5, v96
	v_fmac_f32_e32 v99, 0.5, v97
	v_fmac_f32_e32 v106, 0.5, v90
	v_fmac_f32_e32 v100, 0.5, v91
	v_fmac_f32_e32 v107, 0.5, v92
	v_fmac_f32_e32 v101, 0.5, v93
	v_cvt_pk_bf16_f32 v90, v104, v98
	v_cvt_pk_bf16_f32 v91, v105, v99
	v_cvt_pk_bf16_f32 v92, v106, v100
	v_cvt_pk_bf16_f32 v93, v107, v101
	global_load_dwordx4 v[94:97], v[102:103], off offset:256
	v_lshlrev_b32_e32 v98, 16, v90
	global_store_dwordx4 v[102:103], v[90:93], off
	v_lshlrev_b32_e32 v99, 16, v91
	v_lshlrev_b32_e32 v100, 16, v92
	v_and_b32_e32 v90, 0xffff0000, v90
	v_and_b32_e32 v91, 0xffff0000, v91
	v_and_b32_e32 v92, 0xffff0000, v92
	v_lshlrev_b32_e32 v101, 16, v93
	v_and_b32_e32 v93, 0xffff0000, v93
	v_mul_f32_e32 v90, v90, v90
	v_mul_f32_e32 v91, v91, v91
	v_mul_f32_e32 v92, v92, v92
	v_mul_f32_e32 v93, v93, v93
	v_fmac_f32_e32 v90, v98, v98
	v_fmac_f32_e32 v91, v99, v99
	v_fmac_f32_e32 v92, v100, v100
	v_fmac_f32_e32 v93, v101, v101
	v_add_f32_e32 v90, v90, v91
	v_add_f32_e32 v91, v92, v93
	v_add_f32_e32 v90, v90, v91
	s_waitcnt vmcnt(1)
	v_lshlrev_b32_e32 v91, 16, v94
	v_and_b32_e32 v92, 0xffff0000, v94
	v_and_b32_e32 v94, 0xffff0000, v95
	v_lshlrev_b32_e32 v93, 16, v95
	v_lshlrev_b32_e32 v95, 16, v96
	v_and_b32_e32 v96, 0xffff0000, v96
	v_lshlrev_b32_e32 v98, 16, v97
	v_and_b32_e32 v97, 0xffff0000, v97
	v_fmac_f32_e32 v92, 0.5, v87
	v_fmac_f32_e32 v94, 0.5, v89
	v_fmac_f32_e32 v91, 0.5, v86
	v_fmac_f32_e32 v93, 0.5, v88
	v_fmac_f32_e32 v95, 0.5, v82
	v_fmac_f32_e32 v96, 0.5, v83
	v_fmac_f32_e32 v98, 0.5, v84
	v_fmac_f32_e32 v97, 0.5, v85
	v_cvt_pk_bf16_f32 v84, v91, v92
	v_cvt_pk_bf16_f32 v85, v93, v94
	v_cvt_pk_bf16_f32 v86, v95, v96
	v_cvt_pk_bf16_f32 v87, v98, v97
	global_store_dwordx4 v[102:103], v[84:87], off offset:256
	v_and_b32_e32 v83, 0xffff0000, v84
	v_and_b32_e32 v89, 0xffff0000, v85
	v_and_b32_e32 v92, 0xffff0000, v86
	v_and_b32_e32 v94, 0xffff0000, v87
	v_lshlrev_b32_e32 v82, 16, v84
	v_lshlrev_b32_e32 v88, 16, v85
	v_lshlrev_b32_e32 v91, 16, v86
	v_lshlrev_b32_e32 v93, 16, v87
	v_mul_f32_e32 v83, v83, v83
	v_mul_f32_e32 v89, v89, v89
	v_mul_f32_e32 v92, v92, v92
	v_mul_f32_e32 v94, v94, v94
	v_fmac_f32_e32 v83, v82, v82
	v_fmac_f32_e32 v89, v88, v88
	v_fmac_f32_e32 v92, v91, v91
	v_fmac_f32_e32 v94, v93, v93
	v_add_f32_e32 v82, v83, v89
	v_add_f32_e32 v83, v92, v94
	v_add_f32_e32 v82, v82, v83
	v_add_f32_e32 v82, v90, v82
	ds_bpermute_b32 v83, v122, v82
	s_waitcnt lgkmcnt(0)
	v_add_f32_e32 v82, v82, v83
	ds_bpermute_b32 v83, v116, v82
	s_and_saveexec_b64 s[0:1], s[40:41]
	s_cbranch_execz .LBB0_362
	s_waitcnt lgkmcnt(0)
	v_add_f32_e32 v82, v82, v83
	v_fma_f32 v82, v82, s6, 0.5
	v_trunc_f32_e32 v82, v82
	v_mul_f32_e32 v83, 0x2f800000, v82
	v_floor_f32_e32 v83, v83
	v_fmac_f32_e32 v82, 0xcf800000, v83
	v_cvt_u32_f32_e32 v82, v82
	v_cvt_u32_f32_e32 v83, v83
	v_mov_b32_e32 v172, v82
	v_mov_b32_e32 v173, v83
.LBB0_362:
	s_or_b64 exec, exec, s[0:1]
	v_or_b32_e32 v82, 48, v144
	s_waitcnt lgkmcnt(0)
	v_ashrrev_i32_e32 v83, 31, v82
	v_lshlrev_b64 v[82:83], 12, v[82:83]
	v_lshl_add_u64 v[82:83], s[94:95], 0, v[82:83]
	v_lshl_add_u64 v[86:87], v[142:143], 1, v[82:83]
	v_mov_b32_e32 v82, v190
	v_mov_b32_e32 v83, v191
	v_mov_b32_e32 v84, v192
	v_mov_b32_e32 v85, v193
	v_lshlrev_b32_e32 v88, 16, v82
	v_and_b32_e32 v82, 0xffff0000, v82
	v_lshlrev_b32_e32 v89, 16, v83
	v_and_b32_e32 v83, 0xffff0000, v83
	v_lshlrev_b32_e32 v90, 16, v84
	v_and_b32_e32 v84, 0xffff0000, v84
	v_lshlrev_b32_e32 v91, 16, v85
	v_and_b32_e32 v85, 0xffff0000, v85
	v_fmac_f32_e32 v88, 0.5, v78
	v_fmac_f32_e32 v82, 0.5, v79
	v_fmac_f32_e32 v89, 0.5, v80
	v_fmac_f32_e32 v83, 0.5, v81
	v_fmac_f32_e32 v90, 0.5, v74
	v_fmac_f32_e32 v84, 0.5, v75
	v_fmac_f32_e32 v91, 0.5, v76
	v_fmac_f32_e32 v85, 0.5, v77
	v_cvt_pk_bf16_f32 v74, v88, v82
	v_cvt_pk_bf16_f32 v75, v89, v83
	v_cvt_pk_bf16_f32 v76, v90, v84
	v_cvt_pk_bf16_f32 v77, v91, v85
	global_load_dwordx4 v[78:81], v[86:87], off offset:256
	v_lshlrev_b32_e32 v82, 16, v74
	global_store_dwordx4 v[86:87], v[74:77], off
	v_lshlrev_b32_e32 v83, 16, v75
	v_lshlrev_b32_e32 v84, 16, v76
	v_and_b32_e32 v74, 0xffff0000, v74
	v_and_b32_e32 v75, 0xffff0000, v75
	v_and_b32_e32 v76, 0xffff0000, v76
	v_lshlrev_b32_e32 v85, 16, v77
	v_and_b32_e32 v77, 0xffff0000, v77
	v_mul_f32_e32 v74, v74, v74
	v_mul_f32_e32 v75, v75, v75
	v_mul_f32_e32 v76, v76, v76
	v_mul_f32_e32 v77, v77, v77
	v_fmac_f32_e32 v74, v82, v82
	v_fmac_f32_e32 v75, v83, v83
	v_fmac_f32_e32 v76, v84, v84
	v_fmac_f32_e32 v77, v85, v85
	v_add_f32_e32 v74, v74, v75
	v_add_f32_e32 v75, v76, v77
	v_add_f32_e32 v74, v74, v75
	s_waitcnt vmcnt(1)
	v_lshlrev_b32_e32 v75, 16, v78
	v_and_b32_e32 v76, 0xffff0000, v78
	v_and_b32_e32 v78, 0xffff0000, v79
	v_lshlrev_b32_e32 v77, 16, v79
	v_lshlrev_b32_e32 v79, 16, v80
	v_and_b32_e32 v80, 0xffff0000, v80
	v_lshlrev_b32_e32 v82, 16, v81
	v_and_b32_e32 v81, 0xffff0000, v81
	v_fmac_f32_e32 v76, 0.5, v71
	v_fmac_f32_e32 v78, 0.5, v73
	v_fmac_f32_e32 v75, 0.5, v70
	v_fmac_f32_e32 v77, 0.5, v72
	v_fmac_f32_e32 v79, 0.5, v66
	v_fmac_f32_e32 v80, 0.5, v67
	v_fmac_f32_e32 v82, 0.5, v68
	v_fmac_f32_e32 v81, 0.5, v69
	v_cvt_pk_bf16_f32 v68, v75, v76
	v_cvt_pk_bf16_f32 v69, v77, v78
	v_cvt_pk_bf16_f32 v70, v79, v80
	v_cvt_pk_bf16_f32 v71, v82, v81
	global_store_dwordx4 v[86:87], v[68:71], off offset:256
	v_and_b32_e32 v67, 0xffff0000, v68
	v_and_b32_e32 v73, 0xffff0000, v69
	v_and_b32_e32 v76, 0xffff0000, v70
	v_and_b32_e32 v78, 0xffff0000, v71
	v_lshlrev_b32_e32 v66, 16, v68
	v_lshlrev_b32_e32 v72, 16, v69
	v_lshlrev_b32_e32 v75, 16, v70
	v_lshlrev_b32_e32 v77, 16, v71
	v_mul_f32_e32 v67, v67, v67
	v_mul_f32_e32 v73, v73, v73
	v_mul_f32_e32 v76, v76, v76
	v_mul_f32_e32 v78, v78, v78
	v_fmac_f32_e32 v67, v66, v66
	v_fmac_f32_e32 v73, v72, v72
	v_fmac_f32_e32 v76, v75, v75
	v_fmac_f32_e32 v78, v77, v77
	v_add_f32_e32 v66, v67, v73
	v_add_f32_e32 v67, v76, v78
	v_add_f32_e32 v66, v66, v67
	v_add_f32_e32 v66, v74, v66
	ds_bpermute_b32 v67, v122, v66
	s_waitcnt lgkmcnt(0)
	v_add_f32_e32 v66, v66, v67
	ds_bpermute_b32 v67, v116, v66
	s_and_saveexec_b64 s[0:1], s[40:41]
	s_cbranch_execz .LBB0_364
	s_waitcnt lgkmcnt(0)
	v_add_f32_e32 v66, v66, v67
	v_fma_f32 v66, v66, s6, 0.5
	v_trunc_f32_e32 v66, v66
	v_mul_f32_e32 v67, 0x2f800000, v66
	v_floor_f32_e32 v67, v67
	v_fmac_f32_e32 v66, 0xcf800000, v67
	v_cvt_u32_f32_e32 v66, v66
	v_cvt_u32_f32_e32 v67, v67
	v_mov_b32_e32 v174, v66
	v_mov_b32_e32 v175, v67
.LBB0_364:
	s_or_b64 exec, exec, s[0:1]
	v_add_co_u32_e32 v70, vcc, 0x80000, v140
	s_mov_b64 s[0:1], 0x80000
	s_nop 0
	v_addc_co_u32_e32 v71, vcc, 0, v141, vcc
	s_waitcnt lgkmcnt(0)
	v_mov_b32_e32 v66, v194
	v_mov_b32_e32 v67, v195
	v_mov_b32_e32 v68, v196
	v_mov_b32_e32 v69, v197
	v_lshl_add_u64 v[72:73], v[140:141], 0, s[0:1]
	v_lshlrev_b32_e32 v74, 16, v66
	v_and_b32_e32 v66, 0xffff0000, v66
	v_lshlrev_b32_e32 v75, 16, v67
	v_and_b32_e32 v67, 0xffff0000, v67
	v_lshlrev_b32_e32 v76, 16, v68
	v_and_b32_e32 v68, 0xffff0000, v68
	v_lshlrev_b32_e32 v77, 16, v69
	v_and_b32_e32 v69, 0xffff0000, v69
	v_fmac_f32_e32 v74, 0.5, v62
	v_fmac_f32_e32 v66, 0.5, v63
	v_fmac_f32_e32 v75, 0.5, v64
	v_fmac_f32_e32 v67, 0.5, v65
	v_fmac_f32_e32 v76, 0.5, v58
	v_fmac_f32_e32 v68, 0.5, v59
	v_fmac_f32_e32 v77, 0.5, v60
	v_fmac_f32_e32 v69, 0.5, v61
	v_cvt_pk_bf16_f32 v58, v74, v66
	v_cvt_pk_bf16_f32 v59, v75, v67
	v_cvt_pk_bf16_f32 v60, v76, v68
	v_cvt_pk_bf16_f32 v61, v77, v69
	v_mov_b32_e32 v62, v198
	v_mov_b32_e32 v63, v199
	v_mov_b32_e32 v64, v200
	v_mov_b32_e32 v65, v201
	v_lshlrev_b32_e32 v66, 16, v58
	global_store_dwordx4 v[70:71], v[58:61], off
	v_lshlrev_b32_e32 v67, 16, v59
	v_lshlrev_b32_e32 v68, 16, v60
	v_and_b32_e32 v58, 0xffff0000, v58
	v_and_b32_e32 v59, 0xffff0000, v59
	v_and_b32_e32 v60, 0xffff0000, v60
	v_lshlrev_b32_e32 v69, 16, v61
	v_and_b32_e32 v61, 0xffff0000, v61
	v_mul_f32_e32 v58, v58, v58
	v_mul_f32_e32 v59, v59, v59
	v_mul_f32_e32 v60, v60, v60
	v_mul_f32_e32 v61, v61, v61
	v_fmac_f32_e32 v58, v66, v66
	v_fmac_f32_e32 v59, v67, v67
	v_fmac_f32_e32 v60, v68, v68
	v_fmac_f32_e32 v61, v69, v69
	v_add_f32_e32 v58, v58, v59
	v_add_f32_e32 v59, v60, v61
	v_add_f32_e32 v58, v58, v59
	s_waitcnt vmcnt(1)
	v_lshlrev_b32_e32 v59, 16, v62
	v_and_b32_e32 v60, 0xffff0000, v62
	v_and_b32_e32 v62, 0xffff0000, v63
	v_lshlrev_b32_e32 v61, 16, v63
	v_lshlrev_b32_e32 v63, 16, v64
	v_and_b32_e32 v64, 0xffff0000, v64
	v_lshlrev_b32_e32 v66, 16, v65
	v_and_b32_e32 v65, 0xffff0000, v65
	v_fmac_f32_e32 v60, 0.5, v55
	v_fmac_f32_e32 v62, 0.5, v57
	v_fmac_f32_e32 v59, 0.5, v54
	v_fmac_f32_e32 v61, 0.5, v56
	v_fmac_f32_e32 v63, 0.5, v50
	v_fmac_f32_e32 v64, 0.5, v51
	v_fmac_f32_e32 v66, 0.5, v52
	v_fmac_f32_e32 v65, 0.5, v53
	v_cvt_pk_bf16_f32 v52, v59, v60
	v_cvt_pk_bf16_f32 v53, v61, v62
	v_cvt_pk_bf16_f32 v54, v63, v64
	v_cvt_pk_bf16_f32 v55, v66, v65
	global_store_dwordx4 v[72:73], v[52:55], off offset:256
	v_and_b32_e32 v51, 0xffff0000, v52
	v_and_b32_e32 v57, 0xffff0000, v53
	v_and_b32_e32 v60, 0xffff0000, v54
	v_and_b32_e32 v62, 0xffff0000, v55
	v_lshlrev_b32_e32 v50, 16, v52
	v_lshlrev_b32_e32 v56, 16, v53
	v_lshlrev_b32_e32 v59, 16, v54
	v_lshlrev_b32_e32 v61, 16, v55
	v_mul_f32_e32 v51, v51, v51
	v_mul_f32_e32 v57, v57, v57
	v_mul_f32_e32 v60, v60, v60
	v_mul_f32_e32 v62, v62, v62
	v_fmac_f32_e32 v51, v50, v50
	v_fmac_f32_e32 v57, v56, v56
	v_fmac_f32_e32 v60, v59, v59
	v_fmac_f32_e32 v62, v61, v61
	v_add_f32_e32 v50, v51, v57
	v_add_f32_e32 v51, v60, v62
	v_add_f32_e32 v50, v50, v51
	v_add_f32_e32 v50, v58, v50
	ds_bpermute_b32 v51, v122, v50
	s_waitcnt lgkmcnt(0)
	v_add_f32_e32 v50, v50, v51
	ds_bpermute_b32 v51, v116, v50
	s_and_saveexec_b64 s[0:1], s[40:41]
	s_cbranch_execz .LBB0_366
	s_waitcnt lgkmcnt(0)
	v_add_f32_e32 v50, v50, v51
	v_fma_f32 v50, v50, s6, 0.5
	v_trunc_f32_e32 v50, v50
	v_mul_f32_e32 v51, 0x2f800000, v50
	v_floor_f32_e32 v51, v51
	v_fmac_f32_e32 v50, 0xcf800000, v51
	v_cvt_u32_f32_e32 v50, v50
	v_cvt_u32_f32_e32 v51, v51
	v_mov_b32_e32 v176, v50
	v_mov_b32_e32 v177, v51
.LBB0_366:
	s_or_b64 exec, exec, s[0:1]
	v_add_co_u32_e32 v56, vcc, 0x90000, v140
	s_mov_b64 s[0:1], 0x90000
	s_nop 0
	v_addc_co_u32_e32 v57, vcc, 0, v141, vcc
	v_mov_b32_e32 v52, v202
	v_mov_b32_e32 v53, v203
	v_mov_b32_e32 v54, v204
	v_mov_b32_e32 v55, v205
	s_waitcnt lgkmcnt(0)
	v_lshl_add_u64 v[50:51], v[140:141], 0, s[0:1]
	v_lshlrev_b32_e32 v58, 16, v52
	v_fmac_f32_e32 v58, 0.5, v46
	v_and_b32_e32 v46, 0xffff0000, v52
	v_fmac_f32_e32 v46, 0.5, v47
	v_lshlrev_b32_e32 v47, 16, v53
	v_fmac_f32_e32 v47, 0.5, v48
	v_and_b32_e32 v48, 0xffff0000, v53
	v_fmac_f32_e32 v48, 0.5, v49
	v_cvt_pk_bf16_f32 v46, v58, v46
	v_cvt_pk_bf16_f32 v47, v47, v48
	v_lshlrev_b32_e32 v48, 16, v54
	v_fmac_f32_e32 v48, 0.5, v42
	v_and_b32_e32 v42, 0xffff0000, v54
	v_fmac_f32_e32 v42, 0.5, v43
	v_and_b32_e32 v43, 0xffff0000, v55
	v_cvt_pk_bf16_f32 v48, v48, v42
	v_lshlrev_b32_e32 v42, 16, v55
	v_fmac_f32_e32 v43, 0.5, v45
	v_fmac_f32_e32 v42, 0.5, v44
	v_cvt_pk_bf16_f32 v49, v42, v43
	v_and_b32_e32 v43, 0xffff0000, v46
	v_lshlrev_b32_e32 v42, 16, v46
	v_and_b32_e32 v45, 0xffff0000, v47
	v_mul_f32_e32 v43, v43, v43
	v_lshlrev_b32_e32 v44, 16, v47
	v_fmac_f32_e32 v43, v42, v42
	v_mul_f32_e32 v42, v45, v45
	global_store_dwordx4 v[56:57], v[46:49], off
	v_fmac_f32_e32 v42, v44, v44
	v_add_f32_e32 v42, v43, v42
	v_lshlrev_b32_e32 v46, 16, v48
	v_and_b32_e32 v47, 0xffff0000, v48
	v_lshlrev_b32_e32 v48, 16, v49
	v_and_b32_e32 v49, 0xffff0000, v49
	v_mul_f32_e32 v43, v47, v47
	v_mul_f32_e32 v44, v49, v49
	v_fmac_f32_e32 v43, v46, v46
	v_fmac_f32_e32 v44, v48, v48
	v_add_f32_e32 v43, v43, v44
	v_add_f32_e32 v46, v42, v43
	v_mov_b32_e32 v42, v216
	v_mov_b32_e32 v43, v217
	v_mov_b32_e32 v44, v218
	v_mov_b32_e32 v45, v219
	v_lshlrev_b32_e32 v47, 16, v42
	v_fmac_f32_e32 v47, 0.5, v38
	v_and_b32_e32 v38, 0xffff0000, v42
	v_fmac_f32_e32 v38, 0.5, v39
	v_lshlrev_b32_e32 v39, 16, v43
	v_fmac_f32_e32 v39, 0.5, v40
	v_and_b32_e32 v40, 0xffff0000, v43
	v_fmac_f32_e32 v40, 0.5, v41
	v_cvt_pk_bf16_f32 v38, v47, v38
	v_cvt_pk_bf16_f32 v39, v39, v40
	v_lshlrev_b32_e32 v40, 16, v44
	v_fmac_f32_e32 v40, 0.5, v34
	v_and_b32_e32 v34, 0xffff0000, v44
	v_fmac_f32_e32 v34, 0.5, v35
	v_and_b32_e32 v35, 0xffff0000, v45
	v_cvt_pk_bf16_f32 v40, v40, v34
	v_lshlrev_b32_e32 v34, 16, v45
	v_fmac_f32_e32 v35, 0.5, v37
	v_fmac_f32_e32 v34, 0.5, v36
	v_cvt_pk_bf16_f32 v41, v34, v35
	v_and_b32_e32 v35, 0xffff0000, v38
	v_lshlrev_b32_e32 v34, 16, v38
	v_and_b32_e32 v37, 0xffff0000, v39
	v_mul_f32_e32 v35, v35, v35
	v_lshlrev_b32_e32 v36, 16, v39
	v_fmac_f32_e32 v35, v34, v34
	v_mul_f32_e32 v34, v37, v37
	global_store_dwordx4 v[50:51], v[38:41], off offset:256
	v_fmac_f32_e32 v34, v36, v36
	v_add_f32_e32 v34, v35, v34
	v_lshlrev_b32_e32 v38, 16, v40
	v_and_b32_e32 v39, 0xffff0000, v40
	v_lshlrev_b32_e32 v40, 16, v41
	v_and_b32_e32 v41, 0xffff0000, v41
	v_mul_f32_e32 v35, v39, v39
	v_mul_f32_e32 v36, v41, v41
	v_fmac_f32_e32 v35, v38, v38
	v_fmac_f32_e32 v36, v40, v40
	v_add_f32_e32 v35, v35, v36
	v_add_f32_e32 v34, v34, v35
	v_add_f32_e32 v34, v46, v34
	ds_bpermute_b32 v35, v122, v34
	s_waitcnt lgkmcnt(0)
	v_add_f32_e32 v34, v34, v35
	ds_bpermute_b32 v35, v116, v34
	s_and_saveexec_b64 s[0:1], s[40:41]
	s_cbranch_execz .LBB0_368
	s_waitcnt lgkmcnt(0)
	v_add_f32_e32 v34, v34, v35
	v_fma_f32 v34, v34, s6, 0.5
	v_trunc_f32_e32 v34, v34
	v_mul_f32_e32 v35, 0x2f800000, v34
	v_floor_f32_e32 v35, v35
	v_fmac_f32_e32 v34, 0xcf800000, v35
	v_cvt_u32_f32_e32 v34, v34
	v_cvt_u32_f32_e32 v35, v35
	v_mov_b32_e32 v178, v34
	v_mov_b32_e32 v179, v35
.LBB0_368:
	s_or_b64 exec, exec, s[0:1]
	v_add_co_u32_e32 v40, vcc, 0xa0000, v140
	s_mov_b64 s[0:1], 0xa0000
	s_nop 0
	v_addc_co_u32_e32 v41, vcc, 0, v141, vcc
	v_mov_b32_e32 v36, v220
	v_mov_b32_e32 v37, v221
	v_mov_b32_e32 v38, v222
	v_mov_b32_e32 v39, v223
	s_waitcnt lgkmcnt(0)
	v_lshl_add_u64 v[34:35], v[140:141], 0, s[0:1]
	v_lshlrev_b32_e32 v42, 16, v36
	v_fmac_f32_e32 v42, 0.5, v30
	v_and_b32_e32 v30, 0xffff0000, v36
	v_fmac_f32_e32 v30, 0.5, v31
	v_lshlrev_b32_e32 v31, 16, v37
	v_fmac_f32_e32 v31, 0.5, v32
	v_and_b32_e32 v32, 0xffff0000, v37
	v_fmac_f32_e32 v32, 0.5, v33
	v_cvt_pk_bf16_f32 v30, v42, v30
	v_cvt_pk_bf16_f32 v31, v31, v32
	v_lshlrev_b32_e32 v32, 16, v38
	v_fmac_f32_e32 v32, 0.5, v26
	v_and_b32_e32 v26, 0xffff0000, v38
	v_fmac_f32_e32 v26, 0.5, v27
	v_and_b32_e32 v27, 0xffff0000, v39
	v_cvt_pk_bf16_f32 v32, v32, v26
	v_lshlrev_b32_e32 v26, 16, v39
	v_fmac_f32_e32 v27, 0.5, v29
	v_fmac_f32_e32 v26, 0.5, v28
	v_cvt_pk_bf16_f32 v33, v26, v27
	v_and_b32_e32 v27, 0xffff0000, v30
	v_lshlrev_b32_e32 v26, 16, v30
	v_and_b32_e32 v29, 0xffff0000, v31
	v_mul_f32_e32 v27, v27, v27
	v_lshlrev_b32_e32 v28, 16, v31
	v_fmac_f32_e32 v27, v26, v26
	v_mul_f32_e32 v26, v29, v29
	global_store_dwordx4 v[40:41], v[30:33], off
	v_fmac_f32_e32 v26, v28, v28
	v_add_f32_e32 v26, v27, v26
	v_lshlrev_b32_e32 v30, 16, v32
	v_and_b32_e32 v31, 0xffff0000, v32
	v_lshlrev_b32_e32 v32, 16, v33
	v_and_b32_e32 v33, 0xffff0000, v33
	v_mul_f32_e32 v27, v31, v31
	v_mul_f32_e32 v28, v33, v33
	v_fmac_f32_e32 v27, v30, v30
	v_fmac_f32_e32 v28, v32, v32
	v_add_f32_e32 v27, v27, v28
	v_add_f32_e32 v30, v26, v27
	v_mov_b32_e32 v26, v224
	v_mov_b32_e32 v27, v225
	v_mov_b32_e32 v28, v226
	v_mov_b32_e32 v29, v227
	v_lshlrev_b32_e32 v31, 16, v26
	v_fmac_f32_e32 v31, 0.5, v22
	v_and_b32_e32 v22, 0xffff0000, v26
	v_fmac_f32_e32 v22, 0.5, v23
	v_lshlrev_b32_e32 v23, 16, v27
	v_fmac_f32_e32 v23, 0.5, v24
	v_and_b32_e32 v24, 0xffff0000, v27
	v_fmac_f32_e32 v24, 0.5, v25
	v_cvt_pk_bf16_f32 v22, v31, v22
	v_cvt_pk_bf16_f32 v23, v23, v24
	v_lshlrev_b32_e32 v24, 16, v28
	v_fmac_f32_e32 v24, 0.5, v18
	v_and_b32_e32 v18, 0xffff0000, v28
	v_fmac_f32_e32 v18, 0.5, v19
	v_and_b32_e32 v19, 0xffff0000, v29
	v_cvt_pk_bf16_f32 v24, v24, v18
	v_lshlrev_b32_e32 v18, 16, v29
	v_fmac_f32_e32 v19, 0.5, v21
	v_fmac_f32_e32 v18, 0.5, v20
	v_cvt_pk_bf16_f32 v25, v18, v19
	v_and_b32_e32 v19, 0xffff0000, v22
	v_lshlrev_b32_e32 v18, 16, v22
	v_and_b32_e32 v21, 0xffff0000, v23
	v_mul_f32_e32 v19, v19, v19
	v_lshlrev_b32_e32 v20, 16, v23
	v_fmac_f32_e32 v19, v18, v18
	v_mul_f32_e32 v18, v21, v21
	global_store_dwordx4 v[34:35], v[22:25], off offset:256
	v_fmac_f32_e32 v18, v20, v20
	v_add_f32_e32 v18, v19, v18
	v_lshlrev_b32_e32 v22, 16, v24
	v_and_b32_e32 v23, 0xffff0000, v24
	v_lshlrev_b32_e32 v24, 16, v25
	v_and_b32_e32 v25, 0xffff0000, v25
	v_mul_f32_e32 v19, v23, v23
	v_mul_f32_e32 v20, v25, v25
	v_fmac_f32_e32 v19, v22, v22
	v_fmac_f32_e32 v20, v24, v24
	v_add_f32_e32 v19, v19, v20
	v_add_f32_e32 v18, v18, v19
	v_add_f32_e32 v18, v30, v18
	ds_bpermute_b32 v19, v122, v18
	s_waitcnt lgkmcnt(0)
	v_add_f32_e32 v18, v18, v19
	ds_bpermute_b32 v19, v116, v18
	s_and_saveexec_b64 s[0:1], s[40:41]
	s_cbranch_execz .LBB0_370
	s_waitcnt lgkmcnt(0)
	v_add_f32_e32 v18, v18, v19
	v_fma_f32 v18, v18, s6, 0.5
	v_trunc_f32_e32 v18, v18
	v_mul_f32_e32 v19, 0x2f800000, v18
	v_floor_f32_e32 v19, v19
	v_fmac_f32_e32 v18, 0xcf800000, v19
	v_cvt_u32_f32_e32 v18, v18
	v_cvt_u32_f32_e32 v19, v19
	v_mov_b32_e32 v180, v18
	v_mov_b32_e32 v181, v19
.LBB0_370:
	s_or_b64 exec, exec, s[0:1]
	v_add_co_u32_e32 v22, vcc, 0xb0000, v140
	s_mov_b64 s[0:1], 0xb0000
	s_nop 0
	v_addc_co_u32_e32 v23, vcc, 0, v141, vcc
	s_waitcnt lgkmcnt(0)
	v_mov_b32_e32 v18, v228
	v_mov_b32_e32 v19, v229
	v_mov_b32_e32 v20, v230
	v_mov_b32_e32 v21, v231
	v_lshl_add_u64 v[24:25], v[140:141], 0, s[0:1]
	v_lshlrev_b32_e32 v26, 16, v18
	v_and_b32_e32 v18, 0xffff0000, v18
	v_lshlrev_b32_e32 v27, 16, v19
	v_and_b32_e32 v19, 0xffff0000, v19
	v_lshlrev_b32_e32 v28, 16, v20
	v_and_b32_e32 v20, 0xffff0000, v20
	v_lshlrev_b32_e32 v29, 16, v21
	v_and_b32_e32 v21, 0xffff0000, v21
	v_fmac_f32_e32 v26, 0.5, v14
	v_fmac_f32_e32 v18, 0.5, v15
	v_fmac_f32_e32 v27, 0.5, v16
	v_fmac_f32_e32 v19, 0.5, v17
	v_fmac_f32_e32 v28, 0.5, v10
	v_fmac_f32_e32 v20, 0.5, v11
	v_fmac_f32_e32 v29, 0.5, v12
	v_fmac_f32_e32 v21, 0.5, v13
	v_cvt_pk_bf16_f32 v10, v26, v18
	v_cvt_pk_bf16_f32 v11, v27, v19
	v_cvt_pk_bf16_f32 v12, v28, v20
	v_cvt_pk_bf16_f32 v13, v29, v21
	v_mov_b32_e32 v14, v232
	v_mov_b32_e32 v15, v233
	v_mov_b32_e32 v16, v234
	v_mov_b32_e32 v17, v235
	v_lshlrev_b32_e32 v18, 16, v10
	global_store_dwordx4 v[22:23], v[10:13], off
	v_lshlrev_b32_e32 v19, 16, v11
	v_lshlrev_b32_e32 v20, 16, v12
	v_and_b32_e32 v10, 0xffff0000, v10
	v_and_b32_e32 v11, 0xffff0000, v11
	v_and_b32_e32 v12, 0xffff0000, v12
	v_lshlrev_b32_e32 v21, 16, v13
	v_and_b32_e32 v13, 0xffff0000, v13
	v_mul_f32_e32 v10, v10, v10
	v_mul_f32_e32 v11, v11, v11
	v_mul_f32_e32 v12, v12, v12
	v_mul_f32_e32 v13, v13, v13
	v_fmac_f32_e32 v10, v18, v18
	v_fmac_f32_e32 v11, v19, v19
	v_fmac_f32_e32 v12, v20, v20
	v_fmac_f32_e32 v13, v21, v21
	v_add_f32_e32 v10, v10, v11
	v_add_f32_e32 v11, v12, v13
	v_add_f32_e32 v10, v10, v11
	s_waitcnt vmcnt(1)
	v_lshlrev_b32_e32 v11, 16, v14
	v_and_b32_e32 v12, 0xffff0000, v14
	v_and_b32_e32 v14, 0xffff0000, v15
	v_lshlrev_b32_e32 v13, 16, v15
	v_lshlrev_b32_e32 v15, 16, v16
	v_and_b32_e32 v16, 0xffff0000, v16
	v_lshlrev_b32_e32 v18, 16, v17
	v_and_b32_e32 v17, 0xffff0000, v17
	v_fmac_f32_e32 v12, 0.5, v7
	v_fmac_f32_e32 v14, 0.5, v9
	v_fmac_f32_e32 v11, 0.5, v6
	v_fmac_f32_e32 v13, 0.5, v8
	v_fmac_f32_e32 v15, 0.5, v2
	v_fmac_f32_e32 v16, 0.5, v3
	v_fmac_f32_e32 v18, 0.5, v4
	v_fmac_f32_e32 v17, 0.5, v5
	v_cvt_pk_bf16_f32 v4, v11, v12
	v_cvt_pk_bf16_f32 v5, v13, v14
	v_cvt_pk_bf16_f32 v6, v15, v16
	v_cvt_pk_bf16_f32 v7, v18, v17
	global_store_dwordx4 v[24:25], v[4:7], off offset:256
	v_and_b32_e32 v3, 0xffff0000, v4
	v_and_b32_e32 v9, 0xffff0000, v5
	v_and_b32_e32 v12, 0xffff0000, v6
	v_and_b32_e32 v14, 0xffff0000, v7
	v_lshlrev_b32_e32 v2, 16, v4
	v_lshlrev_b32_e32 v8, 16, v5
	v_lshlrev_b32_e32 v11, 16, v6
	v_lshlrev_b32_e32 v13, 16, v7
	v_mul_f32_e32 v3, v3, v3
	v_mul_f32_e32 v9, v9, v9
	v_mul_f32_e32 v12, v12, v12
	v_mul_f32_e32 v14, v14, v14
	v_fmac_f32_e32 v3, v2, v2
	v_fmac_f32_e32 v9, v8, v8
	v_fmac_f32_e32 v12, v11, v11
	v_fmac_f32_e32 v14, v13, v13
	v_add_f32_e32 v2, v3, v9
	v_add_f32_e32 v3, v12, v14
	v_add_f32_e32 v2, v2, v3
	v_add_f32_e32 v2, v10, v2
	ds_bpermute_b32 v3, v122, v2
	s_waitcnt lgkmcnt(0)
	v_add_f32_e32 v2, v2, v3
	ds_bpermute_b32 v3, v116, v2
	s_and_saveexec_b64 s[0:1], s[40:41]
	s_cbranch_execz .LBB0_372
	s_waitcnt lgkmcnt(0)
	v_add_f32_e32 v2, v2, v3
	v_fma_f32 v2, v2, s6, 0.5
	v_trunc_f32_e32 v2, v2
	v_mul_f32_e32 v3, 0x2f800000, v2
	v_floor_f32_e32 v3, v3
	v_fmac_f32_e32 v2, 0xcf800000, v3
	v_cvt_u32_f32_e32 v2, v2
	v_cvt_u32_f32_e32 v3, v3
	global_atomic_add_x2 v[114:115], v[2:3], off offset:1408
